# gMLP spatial-gating product: the 20 weight-fragment loads issued ahead with counted waits instead of two at a time (load de-serialisation, lever 2)
# baseline (speedup 1.0000x reference)
; #define MFMA32(a, b, c) __builtin_amdgcn_mfma_f32_32x32x16_bf16((a), (b), (c), 0, 0, 0)
; __device__ __forceinline__ void phase4_gmlp(const Args& a, LAS unsigned char* lds) {
;     ...
;     for (int item = blockIdx.x; item < 256; item += gridDim.x) {
;         const int b = item >> 4, ch = item & 15;
;         const size_t tok0 = (size_t)b * 2048 + ch * 128;
;         int tid = tid0; asm volatile("" : "+v"(tid));
;         const int lane = tid & 63, r = lane & 31, h = lane >> 5;
;         __syncthreads();
;         bf16x8_t zf[2][8];
; #pragma unroll
;         for (int dt = 0; dt < 2; ++dt)
; #pragma unroll
;             for (int ks = 0; ks < 8; ++ks) zf[dt][ks] = *(const bf16x8_t*)(zvT + ((((size_t)b * 16 + ch) * 8 + g) * 64 + 32 * dt + r) * 128 + 16 * ks + 8 * h);
;         f32x16 acc[2][4];
; #pragma unroll
;         for (int tt = 0; tt < 4; ++tt) { acc[0][tt] = zero16(); acc[1][tt] = zero16();
;             __builtin_amdgcn_sched_barrier(0);
; #pragma unroll
;             for (int ks = 0; ks < 2 * tt + 2; ++ks) {
;                 const bf16x8_t wf = *(const bf16x8_t*)(Wsp + ((size_t)g * 128 + 32 * tt + r) * 128 + 16 * ks + 8 * h);
;                 acc[0][tt] = MFMA32(zf[0][ks], wf, acc[0][tt]); acc[1][tt] = MFMA32(zf[1][ks], wf, acc[1][tt]);
;             } }
.LBB0_878:
	s_and_b32 s4, s22, 15
	s_ashr_i32 s12, s22, 4
	s_lshl_b32 s23, s4, 7
	s_lshl_b32 s4, s4, 3
	s_ashr_i32 s13, s12, 31
	s_add_i32 s4, s4, s0
	v_mov_b32_e32 v178, v184
	s_lshl_b64 s[24:25], s[12:13], 13
	s_lshl_b64 s[26:27], s[4:5], 6
	s_add_u32 s4, s26, s24
	v_lshrrev_b32_e32 v2, 2, v178
	v_and_b32_e32 v181, 31, v178
	s_addc_u32 s24, s27, s25
	v_and_b32_e32 v182, 8, v2
	v_or_b32_e32 v0, s4, v181
	v_mov_b32_e32 v1, s24
	v_lshlrev_b32_e32 v128, 1, v182
	v_lshl_add_u64 v[2:3], s[2:3], 0, v[128:129]
	v_lshlrev_b64 v[0:1], 8, v[0:1]
	v_lshl_add_u64 v[4:5], v[2:3], 0, v[0:1]
	v_add_co_u32_e32 v8, vcc, s1, v4
	s_waitcnt vmcnt(0) lgkmcnt(0)
	s_nop 0
	v_addc_co_u32_e32 v9, vcc, 0, v5, vcc
	s_barrier
	global_load_dwordx4 v[0:3], v[4:5], off
	global_load_dwordx4 v[130:133], v[4:5], off offset:32
	global_load_dwordx4 v[134:137], v[4:5], off offset:64
	global_load_dwordx4 v[138:141], v[4:5], off offset:96
	global_load_dwordx4 v[142:145], v[4:5], off offset:128
	global_load_dwordx4 v[146:149], v[4:5], off offset:160
	global_load_dwordx4 v[150:153], v[4:5], off offset:192
	global_load_dwordx4 v[154:157], v[4:5], off offset:224
	s_nop 0
	global_load_dwordx4 v[4:7], v[8:9], off
	global_load_dwordx4 v[158:161], v[8:9], off offset:32
	global_load_dwordx4 v[170:173], v[8:9], off offset:64
	global_load_dwordx4 v[174:177], v[8:9], off offset:96
	global_load_dwordx4 v[186:189], v[8:9], off offset:128
	global_load_dwordx4 v[190:193], v[8:9], off offset:160
	global_load_dwordx4 v[194:197], v[8:9], off offset:192
	global_load_dwordx4 v[198:201], v[8:9], off offset:224
	s_lshl_b64 s[12:13], s[12:13], 11
	v_and_b32_e32 v183, 63, v178
	v_lshlrev_b32_e32 v8, 8, v181
	v_mov_b32_e32 v9, v129
	v_lshl_add_u64 v[10:11], s[10:11], 0, v[128:129]
	v_lshl_add_u64 v[16:17], v[10:11], 0, v[8:9]
	v_add_co_u32_e32 v18, vcc, s1, v16
	s_nop 1
	v_addc_co_u32_e32 v19, vcc, 0, v17, vcc
	v_add_co_u32_e32 v202, vcc, s16, v16
	s_nop 1
	v_addc_co_u32_e32 v203, vcc, 0, v17, vcc
	v_add_co_u32_e32 v162, vcc, s17, v16
	s_or_b32 s4, s12, s23
	s_nop 0
	v_addc_co_u32_e32 v163, vcc, 0, v17, vcc
	global_load_dwordx4 v[8:11], v[16:17], off
	global_load_dwordx4 v[12:15], v[16:17], off offset:32
	global_load_dwordx4 v[206:209], v[18:19], off
	global_load_dwordx4 v[210:213], v[18:19], off offset:32
	global_load_dwordx4 v[214:217], v[18:19], off offset:64
	global_load_dwordx4 v[218:221], v[18:19], off offset:96
	global_load_dwordx4 v[222:225], v[202:203], off
	global_load_dwordx4 v[226:229], v[202:203], off offset:32
	global_load_dwordx4 v[230:233], v[202:203], off offset:64
	global_load_dwordx4 v[234:237], v[202:203], off offset:96
	global_load_dwordx4 v[238:241], v[202:203], off offset:128
	global_load_dwordx4 v[242:245], v[202:203], off offset:160
	global_load_dwordx4 v[246:249], v[162:163], off
	global_load_dwordx4 v[250:253], v[162:163], off offset:32
	s_waitcnt vmcnt(13)
	v_mfma_f32_32x32x16_bf16 v[112:127], v[0:3], v[8:11], 0
	v_mfma_f32_32x32x16_bf16 v[96:111], v[4:7], v[8:11], 0
	s_waitcnt vmcnt(12)
	v_mfma_f32_32x32x16_bf16 v[112:127], v[130:133], v[12:15], v[112:127]
	v_mfma_f32_32x32x16_bf16 v[96:111], v[158:161], v[12:15], v[96:111]
	s_waitcnt vmcnt(11)
	v_mfma_f32_32x32x16_bf16 v[80:95], v[0:3], v[206:209], 0
	v_mfma_f32_32x32x16_bf16 v[64:79], v[4:7], v[206:209], 0
	s_waitcnt vmcnt(10)
	v_mfma_f32_32x32x16_bf16 v[80:95], v[130:133], v[210:213], v[80:95]
	v_mfma_f32_32x32x16_bf16 v[64:79], v[158:161], v[210:213], v[64:79]
	s_waitcnt vmcnt(9)
	v_mfma_f32_32x32x16_bf16 v[80:95], v[134:137], v[214:217], v[80:95]
	v_mfma_f32_32x32x16_bf16 v[64:79], v[170:173], v[214:217], v[64:79]
	s_waitcnt vmcnt(8)
	v_mfma_f32_32x32x16_bf16 v[80:95], v[138:141], v[218:221], v[80:95]
	v_mfma_f32_32x32x16_bf16 v[64:79], v[174:177], v[218:221], v[64:79]
	global_load_dwordx4 v[206:209], v[162:163], off offset:64
	global_load_dwordx4 v[210:213], v[162:163], off offset:96
	global_load_dwordx4 v[214:217], v[162:163], off offset:128
	global_load_dwordx4 v[218:221], v[162:163], off offset:160
	s_waitcnt vmcnt(11)
	v_mfma_f32_32x32x16_bf16 v[48:63], v[0:3], v[222:225], 0
	v_mfma_f32_32x32x16_bf16 v[32:47], v[4:7], v[222:225], 0
	s_waitcnt vmcnt(10)
	v_mfma_f32_32x32x16_bf16 v[48:63], v[130:133], v[226:229], v[48:63]
	v_mfma_f32_32x32x16_bf16 v[32:47], v[158:161], v[226:229], v[32:47]
	global_load_dwordx4 v[222:225], v[162:163], off offset:192
	global_load_dwordx4 v[226:229], v[162:163], off offset:224
	s_waitcnt vmcnt(11)
	v_mfma_f32_32x32x16_bf16 v[48:63], v[134:137], v[230:233], v[48:63]
	v_mfma_f32_32x32x16_bf16 v[32:47], v[170:173], v[230:233], v[32:47]
	s_waitcnt vmcnt(10)
	v_mfma_f32_32x32x16_bf16 v[48:63], v[138:141], v[234:237], v[48:63]
	v_mfma_f32_32x32x16_bf16 v[32:47], v[174:177], v[234:237], v[32:47]
	s_waitcnt vmcnt(9)
	v_mfma_f32_32x32x16_bf16 v[48:63], v[142:145], v[238:241], v[48:63]
	v_mfma_f32_32x32x16_bf16 v[32:47], v[186:189], v[238:241], v[32:47]
	s_waitcnt vmcnt(8)
	v_mfma_f32_32x32x16_bf16 v[48:63], v[146:149], v[242:245], v[48:63]
	v_mfma_f32_32x32x16_bf16 v[32:47], v[190:193], v[242:245], v[32:47]
	s_waitcnt vmcnt(7)
	v_mfma_f32_32x32x16_bf16 v[16:31], v[0:3], v[246:249], 0
	v_mfma_f32_32x32x16_bf16 v[0:15], v[4:7], v[246:249], 0
	s_waitcnt vmcnt(6)
	v_mfma_f32_32x32x16_bf16 v[16:31], v[130:133], v[250:253], v[16:31]
	v_mfma_f32_32x32x16_bf16 v[0:15], v[158:161], v[250:253], v[0:15]
	s_waitcnt vmcnt(5)
	v_mfma_f32_32x32x16_bf16 v[16:31], v[134:137], v[206:209], v[16:31]
	v_mfma_f32_32x32x16_bf16 v[0:15], v[170:173], v[206:209], v[0:15]
	s_waitcnt vmcnt(4)
	v_mfma_f32_32x32x16_bf16 v[16:31], v[138:141], v[210:213], v[16:31]
	v_mfma_f32_32x32x16_bf16 v[0:15], v[174:177], v[210:213], v[0:15]
	s_waitcnt vmcnt(3)
; #define LAS __attribute__((address_space(3)))
; #define MFMA32(a, b, c) __builtin_amdgcn_mfma_f32_32x32x16_bf16((a), (b), (c), 0, 0, 0)
; __device__ __forceinline__ void phase4_gmlp(const Args& a, LAS unsigned char* lds) {
;     ...
;         for (int tt = 0; tt < 4; ++tt) { acc[0][tt] = zero16(); acc[1][tt] = zero16();
;             __builtin_amdgcn_sched_barrier(0);
; #pragma unroll
;             for (int ks = 0; ks < 2 * tt + 2; ++ks) {
;                 const bf16x8_t wf = *(const bf16x8_t*)(Wsp + ((size_t)g * 128 + 32 * tt + r) * 128 + 16 * ks + 8 * h);
;                 acc[0][tt] = MFMA32(zf[0][ks], wf, acc[0][tt]); acc[1][tt] = MFMA32(zf[1][ks], wf, acc[1][tt]);
;             } }
;         __builtin_amdgcn_sched_barrier(0);
; #pragma unroll
;         for (int hb = 0; hb < 2; ++hb) {
;             u32x4 zr[8];
; #pragma unroll
;             for (int it = 0; it < 8; ++it) zr[it] = __builtin_nontemporal_load((const u32x4*)(zu + (tok0 + (lane >> 3) + 8 * (8 * hb + it)) * 512 + g * 64 + (lane & 7) * 8));
; #pragma unroll
;             for (int it = 0; it < 8; ++it) { LAS unsigned char* p = tile + ((lane >> 3) + 8 * (8 * hb + it)) * G_TSTR + (lane & 7) * 16;
;                 *(LAS u32x2*)p = (u32x2){zr[it].x, zr[it].y}; *(LAS u32x2*)(p + 8) = (u32x2){zr[it].z, zr[it].w}; }
;         }
	v_mfma_f32_32x32x16_bf16 v[16:31], v[142:145], v[214:217], v[16:31]
	v_mfma_f32_32x32x16_bf16 v[0:15], v[186:189], v[214:217], v[0:15]
	s_waitcnt vmcnt(2)
	v_mfma_f32_32x32x16_bf16 v[16:31], v[146:149], v[218:221], v[16:31]
	v_mfma_f32_32x32x16_bf16 v[0:15], v[190:193], v[218:221], v[0:15]
	s_waitcnt vmcnt(1)
	v_mfma_f32_32x32x16_bf16 v[16:31], v[150:153], v[222:225], v[16:31]
	v_mfma_f32_32x32x16_bf16 v[0:15], v[194:197], v[222:225], v[0:15]
	s_waitcnt vmcnt(0)
	v_mfma_f32_32x32x16_bf16 v[16:31], v[154:157], v[226:229], v[16:31]
	v_mfma_f32_32x32x16_bf16 v[0:15], v[198:201], v[226:229], v[0:15]
	v_bfe_u32 v179, v178, 3, 3
	v_lshlrev_b32_e32 v128, 4, v178
	v_or_b32_e32 v160, s4, v179
	v_and_b32_e32 v128, 0x70, v128
	v_mov_b32_e32 v161, s13
	v_or_b32_e32 v158, 8, v160
	v_mov_b32_e32 v159, s13
	v_lshl_add_u64 v[162:163], s[8:9], 0, v[128:129]
	v_lshlrev_b64 v[130:131], 10, v[160:161]
	v_lshlrev_b64 v[132:133], 10, v[158:159]
	v_lshl_add_u64 v[130:131], v[162:163], 0, v[130:131]
	v_lshl_add_u64 v[132:133], v[162:163], 0, v[132:133]
	v_or_b32_e32 v154, 16, v160
	v_mov_b32_e32 v155, s13
	v_or_b32_e32 v148, 24, v160
	v_mov_b32_e32 v149, s13
	global_load_dwordx4 v[170:173], v[130:131], off nt
	global_load_dwordx4 v[174:177], v[132:133], off nt
	v_lshlrev_b64 v[130:131], 10, v[154:155]
	v_lshlrev_b64 v[132:133], 10, v[148:149]
	v_lshl_add_u64 v[130:131], v[162:163], 0, v[130:131]
	v_lshl_add_u64 v[132:133], v[162:163], 0, v[132:133]
	v_or_b32_e32 v142, 32, v160
	v_mov_b32_e32 v143, s13
	v_or_b32_e32 v136, 40, v160
	v_mov_b32_e32 v137, s13
	global_load_dwordx4 v[186:189], v[130:131], off nt
	global_load_dwordx4 v[190:193], v[132:133], off nt
	v_lshlrev_b64 v[130:131], 10, v[142:143]
	v_lshlrev_b64 v[132:133], 10, v[136:137]
	v_lshl_add_u64 v[130:131], v[162:163], 0, v[130:131]
	v_lshl_add_u64 v[132:133], v[162:163], 0, v[132:133]
	global_load_dwordx4 v[194:197], v[130:131], off nt
	global_load_dwordx4 v[198:201], v[132:133], off nt
	v_or_b32_e32 v132, 48, v160
	v_mov_b32_e32 v133, s13
	v_lshlrev_b64 v[130:131], 10, v[132:133]
	v_lshl_add_u64 v[134:135], v[162:163], 0, v[130:131]
	v_or_b32_e32 v130, 56, v160
	v_mov_b32_e32 v131, s13
	v_lshlrev_b64 v[138:139], 10, v[130:131]
	v_lshl_add_u64 v[138:139], v[162:163], 0, v[138:139]
	v_or_b32_e32 v156, 64, v160
	v_mov_b32_e32 v157, s13
	v_or_b32_e32 v152, 0x48, v160
	v_mov_b32_e32 v153, s13
	global_load_dwordx4 v[202:205], v[134:135], off nt
	global_load_dwordx4 v[206:209], v[138:139], off nt
	v_lshlrev_b64 v[134:135], 10, v[156:157]
	v_lshlrev_b64 v[138:139], 10, v[152:153]
	v_lshl_add_u64 v[134:135], v[162:163], 0, v[134:135]
	v_lshl_add_u64 v[138:139], v[162:163], 0, v[138:139]
	v_or_b32_e32 v150, 0x50, v160
	v_mov_b32_e32 v151, s13
	v_or_b32_e32 v146, 0x58, v160
	v_mov_b32_e32 v147, s13
	global_load_dwordx4 v[210:213], v[134:135], off nt
	global_load_dwordx4 v[214:217], v[138:139], off nt
	v_lshlrev_b64 v[134:135], 10, v[150:151]
	v_lshlrev_b64 v[138:139], 10, v[146:147]
	v_lshl_add_u64 v[134:135], v[162:163], 0, v[134:135]
	v_lshl_add_u64 v[138:139], v[162:163], 0, v[138:139]
	v_or_b32_e32 v144, 0x60, v160
	v_mov_b32_e32 v145, s13
	v_or_b32_e32 v140, 0x68, v160
	v_mov_b32_e32 v141, s13
	global_load_dwordx4 v[218:221], v[134:135], off nt
	global_load_dwordx4 v[222:225], v[138:139], off nt
	v_lshlrev_b64 v[134:135], 10, v[144:145]
	v_lshlrev_b64 v[138:139], 10, v[140:141]
	v_lshl_add_u64 v[134:135], v[162:163], 0, v[134:135]
	v_lshl_add_u64 v[138:139], v[162:163], 0, v[138:139]
	global_load_dwordx4 v[226:229], v[134:135], off nt
	global_load_dwordx4 v[230:233], v[138:139], off nt
	v_or_b32_e32 v138, 0x70, v160
	v_mov_b32_e32 v139, s13
	v_lshlrev_b64 v[134:135], 10, v[138:139]
	v_lshl_add_u64 v[134:135], v[162:163], 0, v[134:135]
	global_load_dwordx4 v[234:237], v[134:135], off nt
	v_or_b32_e32 v134, 0x78, v160
	v_mov_b32_e32 v135, s13
	v_lshlrev_b64 v[238:239], 10, v[134:135]
	v_lshl_add_u64 v[162:163], v[162:163], 0, v[238:239]
	global_load_dwordx4 v[238:241], v[162:163], off nt
	v_add_u32_e32 v180, s14, v128
	v_mad_u32_u24 v162, v179, s18, v180
	v_add_u32_e32 v163, 0x880, v162
	v_readlane_b32 s36, v254, 8
	v_readlane_b32 s40, v254, 12
	v_readlane_b32 s41, v254, 13
	v_add_u32_e32 v185, s14, v182
	s_waitcnt vmcnt(15)
	ds_write2_b64 v162, v[170:171], v[172:173] offset1:1
	s_waitcnt vmcnt(14)
	ds_write2_b64 v162, v[174:175], v[176:177] offset0:136 offset1:137
	v_cmp_lt_i32_e32 vcc, v167, v168
	v_readlane_b32 s37, v254, 9
	v_readlane_b32 s38, v254, 10
	v_cndmask_b32_e32 v182, v166, v167, vcc
	v_lshlrev_b32_e32 v182, 2, v182
	v_cmp_gt_u32_e32 vcc, 32, v183
	v_readlane_b32 s39, v254, 11
	s_waitcnt vmcnt(13)
	ds_write2_b64 v163, v[186:187], v[188:189] offset1:1
	v_add_u32_e32 v163, 0xcc0, v162
	v_add_u32_e32 v162, 0x1100, v162
	s_waitcnt vmcnt(12)
	ds_write2_b64 v163, v[190:191], v[192:193] offset1:1
	v_mov_b32_e32 v163, v129
	s_waitcnt vmcnt(11)
	ds_write2_b64 v162, v[194:195], v[196:197] offset1:1
	v_mad_u32_u24 v162, v179, s18, v164
	v_add_u32_e32 v177, v180, v162
	v_mad_u32_u24 v162, v179, s18, v165
	v_add_u32_e32 v173, v180, v162
	v_add_u32_e32 v176, 0x880, v177
	v_add_u32_e32 v175, 0xcc0, v177
	v_add_u32_e32 v174, 0x1100, v177
	v_add_u32_e32 v172, 0x880, v173
	v_add_u32_e32 v171, 0xcc0, v173
	v_add_u32_e32 v170, 0x1100, v173
	v_add_u32_e32 v178, 0x1540, v173
	s_waitcnt vmcnt(10)
	ds_write2_b64 v177, v[198:199], v[200:201] offset1:1
	s_waitcnt vmcnt(9)
	ds_write2_b64 v177, v[202:203], v[204:205] offset0:136 offset1:137
	s_waitcnt vmcnt(8)
	ds_write2_b64 v176, v[206:207], v[208:209] offset1:1
	v_or_b32_e32 v162, s15, v181
	v_lshl_add_u64 v[186:187], v[162:163], 2, s[40:41]
	v_mad_u32_u24 v163, v181, s18, v185
	v_readlane_b32 s42, v254, 14
	v_readlane_b32 s43, v254, 15
	v_readlane_b32 s44, v254, 16
	v_readlane_b32 s45, v254, 17
	s_waitcnt vmcnt(7)
; #define LAS __attribute__((address_space(3)))
; __device__ __forceinline__ void phase4_gmlp(const Args& a, LAS unsigned char* lds) {
;     ...
;             for (int it = 0; it < 8; ++it) { LAS unsigned char* p = tile + ((lane >> 3) + 8 * (8 * hb + it)) * G_TSTR + (lane & 7) * 16;
;                 *(LAS u32x2*)p = (u32x2){zr[it].x, zr[it].y}; *(LAS u32x2*)(p + 8) = (u32x2){zr[it].z, zr[it].w}; }
;         }
;         asm volatile("s_waitcnt lgkmcnt(0)" ::: "memory");
; #pragma unroll
;         for (int tt = 0; tt < 4; ++tt) {
;             const int tl = 32 * tt + r;
;             const float bias = sp_b[g * 128 + tl];
;             float ss = 0.f;
; #pragma unroll
;             for (int dt = 0; dt < 2; ++dt)
; #pragma unroll
;                 for (int ap = 0; ap < 4; ++ap) {
;                     const u32x2 zz = *(const LAS u32x2*)(tile + tl * G_TSTR + (32 * dt + 8 * ap + 4 * h) * 2);
;                     const float z0 = __uint_as_float(zz.x << 16), z1 = __uint_as_float(zz.x & 0xffff0000u), z2 = __uint_as_float(zz.y << 16), z3 = __uint_as_float(zz.y & 0xffff0000u);
;                     float v0 = z0 * (acc[dt][tt][4 * ap] + bias), v1 = z1 * (acc[dt][tt][4 * ap + 1] + bias), v2 = z2 * (acc[dt][tt][4 * ap + 2] + bias), v3 = z3 * (acc[dt][tt][4 * ap + 3] + bias);
;                     acc[dt][tt][4 * ap] = v0; acc[dt][tt][4 * ap + 1] = v1; acc[dt][tt][4 * ap + 2] = v2; acc[dt][tt][4 * ap + 3] = v3;
;                     ss += (v0 * v0 + v1 * v1) + (v2 * v2 + v3 * v3);
;                 }
;             ss += __shfl_xor(ss, 32);
;             if (h == 0) SSQ2[g * 128 + tl] = ss;
	ds_write2_b64 v175, v[210:211], v[212:213] offset1:1
	s_waitcnt vmcnt(6)
	ds_write2_b64 v174, v[214:215], v[216:217] offset1:1
	s_waitcnt vmcnt(5)
	ds_write2_b64 v173, v[218:219], v[220:221] offset1:1
	s_waitcnt vmcnt(4)
	ds_write2_b64 v173, v[222:223], v[224:225] offset0:136 offset1:137
	v_readlane_b32 s46, v254, 18
	v_readlane_b32 s47, v254, 19
	v_readlane_b32 s48, v254, 20
	s_waitcnt vmcnt(3)
	ds_write2_b64 v172, v[226:227], v[228:229] offset1:1
	s_waitcnt vmcnt(2)
	ds_write2_b64 v171, v[230:231], v[232:233] offset1:1
	v_readlane_b32 s49, v254, 21
	v_readlane_b32 s50, v254, 22
	v_readlane_b32 s51, v254, 23
	s_waitcnt vmcnt(1)
	ds_write2_b64 v170, v[234:235], v[236:237] offset1:1
	s_waitcnt vmcnt(0)
	ds_write2_b64 v178, v[238:239], v[240:241] offset1:1
	s_waitcnt lgkmcnt(0)
	global_load_dword v198, v[186:187], off
	ds_read2_b64 v[186:189], v163 offset1:2
	ds_read2_b64 v[190:193], v163 offset0:4 offset1:6
	ds_read2_b64 v[194:197], v163 offset0:8 offset1:10
	s_waitcnt lgkmcnt(2)
	v_lshlrev_b32_e32 v200, 16, v186
	v_and_b32_e32 v201, 0xffff0000, v186
	v_lshlrev_b32_e32 v186, 16, v187
	v_and_b32_e32 v187, 0xffff0000, v187
	v_lshlrev_b32_e32 v202, 16, v188
	v_and_b32_e32 v203, 0xffff0000, v188
	v_lshlrev_b32_e32 v188, 16, v189
	v_and_b32_e32 v189, 0xffff0000, v189
	s_waitcnt lgkmcnt(1)
	v_lshlrev_b32_e32 v204, 16, v190
	v_and_b32_e32 v205, 0xffff0000, v190
	v_lshlrev_b32_e32 v190, 16, v191
	v_and_b32_e32 v191, 0xffff0000, v191
	v_lshlrev_b32_e32 v206, 16, v192
	v_and_b32_e32 v207, 0xffff0000, v192
	v_lshlrev_b32_e32 v192, 16, v193
	v_and_b32_e32 v193, 0xffff0000, v193
	s_waitcnt lgkmcnt(0)
	v_lshlrev_b32_e32 v208, 16, v194
	v_and_b32_e32 v209, 0xffff0000, v194
	s_waitcnt vmcnt(0)
	v_pk_add_f32 v[114:115], v[114:115], v[198:199] op_sel_hi:[1,0]
	v_pk_add_f32 v[214:215], v[124:125], v[198:199] op_sel_hi:[1,0]
	v_pk_mul_f32 v[124:125], v[114:115], v[186:187]
	v_lshlrev_b32_e32 v186, 16, v195
	v_and_b32_e32 v187, 0xffff0000, v195
	v_pk_add_f32 v[98:99], v[98:99], v[198:199] op_sel_hi:[1,0]
	v_pk_add_f32 v[100:101], v[100:101], v[198:199] op_sel_hi:[1,0]
	v_pk_mul_f32 v[98:99], v[98:99], v[186:187]
	v_lshlrev_b32_e32 v186, 16, v196
	v_and_b32_e32 v187, 0xffff0000, v196
	v_lshlrev_b32_e32 v196, 16, v197
	v_and_b32_e32 v197, 0xffff0000, v197
	v_pk_add_f32 v[102:103], v[102:103], v[198:199] op_sel_hi:[1,0]
	v_pk_add_f32 v[116:117], v[116:117], v[198:199] op_sel_hi:[1,0]
	v_pk_add_f32 v[118:119], v[118:119], v[198:199] op_sel_hi:[1,0]
	v_pk_add_f32 v[210:211], v[120:121], v[198:199] op_sel_hi:[1,0]
	v_pk_add_f32 v[212:213], v[122:123], v[198:199] op_sel_hi:[1,0]
	v_pk_mul_f32 v[100:101], v[100:101], v[186:187]
	v_pk_mul_f32 v[102:103], v[102:103], v[196:197]
	v_pk_add_f32 v[112:113], v[112:113], v[198:199] op_sel_hi:[1,0]
	v_pk_mul_f32 v[122:123], v[116:117], v[202:203]
	v_pk_mul_f32 v[120:121], v[118:119], v[188:189]
	v_pk_mul_f32 v[118:119], v[210:211], v[204:205]
	v_pk_mul_f32 v[116:117], v[212:213], v[190:191]
	v_pk_mul_f32 v[114:115], v[214:215], v[206:207]
	v_pk_mul_f32 v[196:197], v[100:101], v[100:101]
	v_pk_mul_f32 v[214:215], v[102:103], v[102:103]
	v_pk_add_f32 v[216:217], v[126:127], v[198:199] op_sel_hi:[1,0]
	v_pk_mul_f32 v[126:127], v[112:113], v[200:201]
	v_pk_mul_f32 v[204:205], v[118:119], v[118:119]
	v_pk_mul_f32 v[206:207], v[116:117], v[116:117]
	ds_read2_b64 v[186:189], v163 offset0:12 offset1:14
	v_add_f32_e32 v163, v214, v215
	v_add_f32_e32 v196, v196, v197
	v_pk_mul_f32 v[112:113], v[216:217], v[192:193]
	v_pk_mul_f32 v[190:191], v[126:127], v[126:127]
	v_pk_mul_f32 v[192:193], v[124:125], v[124:125]
	v_pk_mul_f32 v[200:201], v[122:123], v[122:123]
	v_pk_mul_f32 v[202:203], v[120:121], v[120:121]
	v_add_f32_e32 v163, v196, v163
	v_add_f32_e32 v196, v206, v207
	v_add_f32_e32 v197, v204, v205
	v_add_f32_e32 v196, v197, v196
	v_add_f32_e32 v197, v202, v203
	v_add_f32_e32 v200, v200, v201
	v_add_f32_e32 v192, v192, v193
	v_add_f32_e32 v190, v190, v191
	v_pk_mul_f32 v[210:211], v[114:115], v[114:115]
	v_pk_mul_f32 v[212:213], v[112:113], v[112:113]
	v_pk_add_f32 v[96:97], v[96:97], v[198:199] op_sel_hi:[1,0]
	v_add_f32_e32 v197, v200, v197
	v_add_f32_e32 v190, v190, v192
	v_pk_mul_f32 v[96:97], v[96:97], v[208:209]
	v_add_f32_e32 v190, v190, v197
	v_add_f32_e32 v191, v212, v213
	v_add_f32_e32 v192, v210, v211
	v_pk_mul_f32 v[194:195], v[96:97], v[96:97]
	v_pk_mul_f32 v[208:209], v[98:99], v[98:99]
	v_add_f32_e32 v190, v190, v196
	v_add_f32_e32 v191, v192, v191
	s_waitcnt lgkmcnt(0)
	v_lshlrev_b32_e32 v216, 16, v186
	v_and_b32_e32 v217, 0xffff0000, v186
	v_pk_add_f32 v[104:105], v[104:105], v[198:199] op_sel_hi:[1,0]
	v_lshlrev_b32_e32 v186, 16, v187
	v_and_b32_e32 v187, 0xffff0000, v187
	v_pk_add_f32 v[106:107], v[106:107], v[198:199] op_sel_hi:[1,0]
	v_add_f32_e32 v190, v190, v191
	v_add_f32_e32 v191, v208, v209
	v_add_f32_e32 v192, v194, v195
	v_pk_mul_f32 v[104:105], v[104:105], v[216:217]
	v_pk_mul_f32 v[106:107], v[106:107], v[186:187]
	v_add_f32_e32 v191, v192, v191
	v_pk_mul_f32 v[186:187], v[104:105], v[104:105]
	v_pk_mul_f32 v[216:217], v[106:107], v[106:107]
	v_lshlrev_b32_e32 v218, 16, v188
	v_and_b32_e32 v219, 0xffff0000, v188
	v_pk_add_f32 v[108:109], v[108:109], v[198:199] op_sel_hi:[1,0]
	v_lshlrev_b32_e32 v188, 16, v189
	v_and_b32_e32 v189, 0xffff0000, v189
	v_pk_add_f32 v[110:111], v[110:111], v[198:199] op_sel_hi:[1,0]
	v_add_f32_e32 v190, v190, v191
	v_pk_mul_f32 v[108:109], v[108:109], v[218:219]
	v_pk_mul_f32 v[110:111], v[110:111], v[188:189]
	v_add_f32_e32 v163, v190, v163
	v_add_f32_e32 v190, v216, v217
	v_add_f32_e32 v186, v186, v187
	v_pk_mul_f32 v[188:189], v[108:109], v[108:109]
	v_pk_mul_f32 v[198:199], v[110:111], v[110:111]
	v_add_f32_e32 v186, v186, v190
	v_add_f32_e32 v163, v163, v186
	v_add_f32_e32 v186, v198, v199
	v_add_f32_e32 v187, v188, v189
	v_add_f32_e32 v186, v187, v186
	v_add_f32_e32 v163, v163, v186
	ds_bpermute_b32 v186, v182, v163
	s_and_saveexec_b64 s[12:13], vcc
	s_cbranch_execz .LBB0_880
	v_lshl_add_u32 v162, v162, 2, 0
	s_waitcnt lgkmcnt(0)
	v_add_f32_e32 v163, v163, v186
	v_add_u32_e32 v162, 0x22000, v162
	ds_write_b32 v162, v163
